# phase 0: five-way rotation of each workgroup's unit list (group (bid>>3)%5 starts at its k-th unit and wraps) instead of the two-way reversal
# speedup vs baseline: 1.0012x; 1.0012x over previous
.LBB0_5:
	s_or_b64 exec, exec, s[6:7]
	s_load_dwordx16 s[8:23], s[0:1], 0x40
	s_load_dwordx16 s[80:95], s[0:1], 0x80
	s_cmp_lt_i32 s68, 1
	s_cselect_b64 s[6:7], -1, 0
	s_cmp_gt_i32 s69, 0
	s_waitcnt lgkmcnt(0)
	v_writelane_b32 v240, s8, 6
	s_nop 1
	v_writelane_b32 v240, s9, 7
	v_writelane_b32 v240, s10, 8
	v_writelane_b32 v240, s11, 9
	v_writelane_b32 v240, s12, 10
	v_writelane_b32 v240, s13, 11
	v_writelane_b32 v240, s14, 12
	v_writelane_b32 v240, s15, 13
	v_writelane_b32 v240, s16, 14
	v_writelane_b32 v240, s17, 15
	v_writelane_b32 v240, s18, 16
	v_writelane_b32 v240, s19, 17
	v_writelane_b32 v240, s20, 18
	v_writelane_b32 v240, s21, 19
	v_writelane_b32 v240, s22, 20
	v_writelane_b32 v240, s23, 21
	s_cselect_b64 s[8:9], -1, 0
	s_and_b64 s[52:53], s[6:7], s[8:9]
	s_andn2_b64 vcc, exec, s[52:53]
	s_cbranch_vccnz .LBB0_68
	s_cmpk_gt_i32 s2, 0x510
	s_cbranch_scc1 .LBB0_68
	v_add_u32_e32 v3, -1, v1
	v_and_b32_e32 v2, 63, v1
	v_and_b32_e32 v3, 15, v3
	v_lshlrev_b32_e32 v54, 2, v2
	v_cvt_f32_ubyte0_e32 v3, v3
	v_mov_b32_e32 v102, 0x38d1b717
	v_add_u32_e32 v101, 0, v54
	v_fmac_f32_e32 v102, 0x3f7fff90, v3
	v_and_b32_e32 v3, 0x3c0, v1
	v_and_b32_e32 v107, 31, v1
	v_and_b32_e32 v5, 0x3e0, v1
	v_lshl_add_u32 v106, v3, 2, v101
	v_lshrrev_b32_e32 v3, 5, v1
	v_lshlrev_b32_e32 v5, 2, v5
	v_lshlrev_b32_e32 v6, 2, v107
	s_add_u32 s54, s66, 0x1400000
	v_lshl_add_u32 v108, v3, 8, 0
	v_add3_u32 v109, 0, v5, v6
	v_mul_u32_u24_e32 v5, 0x700, v3
	s_addc_u32 s55, s67, 0
	v_add3_u32 v110, v108, v5, v6
	v_mul_u32_u24_e32 v5, 0x1800, v3
	s_add_u32 s28, s66, 0x1600000
	v_or_b32_e32 v111, v5, v107
	v_lshlrev_b32_e32 v5, 4, v1
	s_addc_u32 s29, s67, 0
	s_load_dwordx16 s[12:27], s[0:1], 0x0
	v_and_b32_e32 v8, 0x3f0, v5
	v_lshlrev_b32_e32 v5, 5, v1
	s_add_u32 s96, s66, 0x1800000
	v_lshrrev_b32_e32 v113, 1, v1
	v_and_b32_e32 v56, 32, v5
	s_addc_u32 s97, s67, 0
	v_mov_b32_e32 v55, 0
	v_lshlrev_b32_e32 v5, 2, v113
	v_mul_u32_u24_e32 v7, 0x404, v56
	s_add_u32 s72, s66, 0x1a00000
	v_lshlrev_b32_e32 v4, 2, v1
	v_add3_u32 v114, 0, v5, v7
	s_addc_u32 s73, s67, 0
	v_mov_b32_e32 v9, v55
	v_mov_b32_e32 v5, v55
	v_writelane_b32 v240, s3, 22
	v_add_u32_e32 v112, 0, v8
	s_add_u32 s33, s66, 0x1a80000
	v_lshl_add_u64 v[66:67], s[94:95], 0, v[8:9]
	v_lshl_add_u64 v[68:69], s[92:93], 0, v[8:9]
	v_lshl_add_u64 v[70:71], s[90:91], 0, v[8:9]
	s_waitcnt lgkmcnt(0)
	v_lshl_add_u64 v[72:73], s[26:27], 0, v[8:9]
	v_lshl_add_u64 v[8:9], s[66:67], 0, v[4:5]
	s_mov_b64 s[8:9], 0x1a20000
	v_lshrrev_b32_e32 v57, 6, v1
	s_movk_i32 s6, 0xa0
	v_mul_u32_u24_e32 v3, 0x60000, v3
	s_addc_u32 s3, s67, 0
	v_readlane_b32 s36, v240, 6
	v_mov_b32_e32 v7, v55
	v_lshl_add_u64 v[82:83], v[8:9], 0, s[8:9]
	s_movk_i32 s8, 0xf000
	v_mad_u32_u24 v104, v57, s6, 0
	s_movk_i32 s6, 0x60
	s_add_u32 s57, s66, 0x1a40000
	v_readlane_b32 s37, v240, 7
	v_readlane_b32 s44, v240, 14
	v_readlane_b32 s45, v240, 15
	v_readlane_b32 s46, v240, 16
	v_readlane_b32 s47, v240, 17
	v_readlane_b32 s48, v240, 18
	v_readlane_b32 s49, v240, 19
	v_readlane_b32 s50, v240, 20
	v_readlane_b32 s51, v240, 21
	v_lshl_add_u64 v[6:7], s[22:23], 0, v[6:7]
	v_lshlrev_b32_e32 v10, 2, v3
	v_mov_b32_e32 v11, v55
	v_lshl_add_u32 v3, v57, 8, 0
	v_lshl_add_u64 v[8:9], s[18:19], 0, v[4:5]
	s_mov_b32 s9, -1
	s_mov_b32 s18, 0x54442d18
	v_or_b32_e32 v100, 0xffffc000, v57
	v_mul_u32_u24_e32 v103, 0xa0, v57
	v_add_u32_e32 v105, 0, v4
	v_cmp_gt_u32_e64 s[6:7], s6, v1
	s_addc_u32 s74, s67, 0
	v_lshl_add_u64 v[58:59], s[46:47], 0, v[54:55]
	v_lshl_add_u64 v[60:61], s[84:85], 0, v[54:55]
	v_lshl_add_u64 v[62:63], s[50:51], 0, v[54:55]
	v_lshl_add_u64 v[64:65], s[82:83], 0, v[54:55]
	v_lshl_add_u64 v[74:75], s[44:45], 0, v[54:55]
	s_movk_i32 s56, 0x1000
	v_add_u32_e32 v115, 0x1000, v3
	v_lshl_add_u64 v[76:77], s[48:49], 0, v[54:55]
	v_add_u32_e32 v116, 0x2000, v3
	v_lshl_add_u64 v[78:79], s[80:81], 0, v[54:55]
	v_lshl_add_u64 v[80:81], s[36:37], 0, v[4:5]
	v_lshl_add_u64 v[84:85], v[8:9], 0, s[8:9]
	v_lshl_add_u64 v[86:87], s[20:21], 0, v[4:5]
	s_mov_b32 s19, 0x401921fb
	v_lshlrev_b32_e32 v88, 1, v2
	v_mul_u32_u24_e32 v117, 0x404, v57
	v_add_u32_e32 v118, 0xfffffe00, v1
	v_mov_b32_e32 v119, 0x1000
	v_mov_b32_e32 v120, 0x100
	v_mov_b32_e32 v121, 0xffffff08
	v_mov_b32_e32 v122, 0x80000
	v_mov_b32_e32 v123, 0x8000
	v_mov_b32_e32 v124, 0x7f800000
	v_lshl_add_u64 v[90:91], v[6:7], 0, v[10:11]
	s_mov_b32 s21, 0x10e000
	s_mov_b32 s20, 0x114000
	s_mov_b32 s22, 0x11a000
	s_mov_b32 s58, 0x120000
	s_mov_b32 s59, 0x126000
	s_mov_b32 s60, 0x12c000
	s_mov_b32 s61, 0x132000
	s_mov_b32 s62, 0x138000
	s_mov_b32 s63, 0x13e000
	s_mov_b32 s75, 0x144000
	s_mov_b32 s76, 0x14a000
	s_mov_b32 s77, 0x150000
	s_mov_b32 s78, 0x156000
	s_mov_b32 s79, 0x15c000
	s_mov_b32 s80, 0x162000
	s_mov_b32 s81, 0x168000
	s_mov_b32 s82, 0x16e000
	s_mov_b32 s83, 0x174000
	s_mov_b32 s84, 0x17a000
	s_mov_b32 s85, 0xa000
	s_mov_b32 s90, s2
	s_mov_b32 s92, 0
	s_cmpk_lg_u32 s70, 0x100
	s_cbranch_scc1 .Lp0_order
	s_movk_i32 s92, 5
	s_cmpk_gt_u32 s2, 16
	s_cbranch_scc1 .Lp0_five
	s_movk_i32 s92, 6
.Lp0_five:
	s_lshl_b32 s91, s92, 8
	s_lshr_b32 s93, s2, 3
	s_mul_i32 s94, s93, 52
	s_lshr_b32 s94, s94, 8
	s_mul_i32 s94, s94, 5
	s_sub_i32 s93, s93, s94
	s_lshl_b32 s93, s93, 8
	s_add_i32 s90, s90, s93

.LBB0_8:
	s_cmp_eq_u32 s92, 0
	s_cbranch_scc1 .Lp0_plain
	s_addk_i32 s90, 0x100
	s_cmpk_lt_u32 s90, 0x511
	s_cbranch_scc1 .Lp0_nowrap
	s_sub_i32 s90, s90, s91
.Lp0_nowrap:
	s_add_i32 s92, s92, -1
	s_cmp_eq_u32 s92, 0
	s_cbranch_scc1 .LBB0_67
	s_branch .LBB0_9
